# P2: K tile LDS rows chunk-swizzled (16B chunk ^1 for rows 4..11 mod 16) so ds_read_b128 lane groups are bank-conflict-free
# speedup vs baseline: 1.0179x; 1.0120x over previous
; #define LAS __attribute__((address_space(3)))
; #define ATT_QPTR(I, i_) (Z + ((size_t)((I).qslot0() + ((I).isA ? ((wave * 4 + (i_)) >> 3) : 0)) * TT + (I).seq0 + (I).res * (I).Lr + (I).j0 + 16 * ATT_QT(I, i_) + qi) * 64)
;     ...
;     LAS const unsigned char* kp = ldsK + (kstart + qi) * KRS + g * 16;
;     ...
;     const int nloc = nA + nB, r0 = tid >> 3, ch = tid & 7;
;     v4u pk[6], pv[6];
;     ...
;     if (nloc <= 0) return;
;     Item cur = decode(0, na0, nA, nb0), nxt = cur;
;     ...
;     bf16x8 q0, q1;
;     { const bf16* qp = ATT_QPTR(cur, 0); q0 = *(const bf16x8*)(qp + g * 8); q1 = *(const bf16x8*)(qp + 32 + g * 8); }
;     asm volatile("" ::: "memory");
;     ATT_ISSUE(cur);
;     int tkey = -1;
;     for (int k = 0; k < nloc; ++k) {
;         __syncthreads();
; #pragma unroll
;         for (int i = 0; i < 6; ++i) { const int row = r0 + 64 * i; *(LAS v4u*)(ldsK + row * KRS + ch * 16) = pk[i]; *(LAS v4u*)(ldsV + row * VRS + ch * 16) = pv[i];
;             if (ch == 0) { const unsigned kp = (unsigned)(cur.j0 - cur.n() + row); const float ninf = -__builtin_inff();
;                 pmt[row] = (kp < (unsigned)(cur.pair ? cur.Lr : cur.Lre)) ? 0.f : ninf;
;                 pmt[NKS_MAX + row] = (cur.pair ? (kp - (unsigned)cur.Lr < (unsigned)cur.Lr) : (kp < (unsigned)cur.Lre)) ? 0.f : ninf; } }
.LBB0_178:
	s_or_b64 exec, exec, s[8:9]
	v_lshlrev_b32_e32 v0, 3, v144
	v_and_b32_e32 v0, 24, v0
	v_mov_b32_e32 v63, v21
	s_movk_i32 s78, 0x90
	s_movk_i32 s79, 0xa0
	v_lshl_add_u32 v175, v117, 4, 0
	v_lshlrev_b32_e32 v148, 2, v116
	v_add_u32_e32 v150, 0, v0
	v_lshl_add_u64 v[152:153], s[20:21], 0, v[62:63]
	v_mul_lo_u32 v0, v151, s78
	v_mul_lo_u32 v63, v151, s79
	s_add_i32 s0, 0, 0x1f000
	v_add_u32_e32 v180, 64, v151
	v_add_u32_e32 v1, 0x2800, v63
	v_add_u32_e32 v182, 0x80, v151
	v_add_u32_e32 v2, 0x5000, v63
	v_add_u32_e32 v184, 0xc0, v151
	v_add_u32_e32 v3, 0x7800, v63
	v_add_u32_e32 v186, 0x100, v151
	v_add_u32_e32 v4, 0xa000, v63
	v_add_u32_e32 v188, 0x140, v151
	v_add_u32_e32 v5, 0xc800, v63
	v_sub_u32_e32 v6, v148, v144
	v_add_u32_e32 v242, 4, v151
	v_bfe_u32 v242, v242, 3, 1
	v_xor_b32_e32 v242, v242, v117
	v_lshl_add_u32 v193, v242, 4, v0
	v_mbcnt_lo_u32_b32 v0, -1, 0
	v_mov_b32_e32 v145, v16
	v_cmp_ne_u32_e64 s[8:9], 0, v117
	s_lshl_b32 s77, s49, 2
	v_add_u32_e32 v243, 4, v144
	v_bfe_u32 v243, v243, 3, 1
	v_xor_b32_e32 v243, v243, v116
	v_lshlrev_b32_e32 v146, 4, v243
	v_lshrrev_b32_e32 v178, 2, v144
	v_mov_b32_e32 v149, v21
	v_cmp_eq_u32_e64 s[4:5], 0, v116
	v_lshl_add_u32 v179, v151, 2, s0
	v_lshl_add_u32 v181, v180, 2, s0
	v_lshl_add_u32 v183, v182, 2, s0
	v_lshl_add_u32 v185, v184, 2, s0
	v_lshl_add_u32 v187, v186, 2, s0
	v_lshl_add_u32 v189, v188, 2, s0
	s_lshl_b32 s80, s49, 1
	v_subrev_u32_e32 v190, s73, v6
	s_mov_b32 s66, -1
	s_mov_b32 s81, 0xff800000
	v_add_u32_e32 v191, v175, v2
	v_add_u32_e32 v192, v175, v4
	s_movk_i32 s82, 0x280
	s_add_i32 s83, 0, 0x1c800
	v_add_u32_e32 v194, v175, v1
	v_mov_b32_e32 v195, 0xff800000
	v_add_u32_e32 v197, v175, v3
	v_add_u32_e32 v198, v175, v5
	v_mov_b32_e32 v56, 0
	v_mbcnt_hi_u32_b32 v199, -1, v0
	v_mov_b32_e32 v200, 0x42000000
	s_mov_b32 s84, 0
	s_branch .LBB0_180
